# grid barrier: non-leader workgroups poll the cross-XCD release word directly; per-XCD release bump removed
# speedup vs baseline: 1.0554x; 1.0077x over previous
; __device__ __forceinline__ unsigned xb_ld(unsigned* p)              { return __hip_atomic_load(p, __ATOMIC_RELAXED, __HIP_MEMORY_SCOPE_AGENT); }
; __device__ __forceinline__ unsigned xb_add(unsigned* p, unsigned v) { return __hip_atomic_fetch_add(p, v, __ATOMIC_RELAXED, __HIP_MEMORY_SCOPE_AGENT); }
; #define XB_SPIN(cond, bar) do { unsigned _sp = 0; while (cond) { __builtin_amdgcn_s_sleep(1); \
;     if ((++_sp & 255u) == 0u) { if (xb_ld(&(bar)[XB_TMO])) break; if (_sp > XB_SPIN_CAP) { atomicAdd(&(bar)[XB_TMO], 1u); break; } } } } while (0)
; __device__ __forceinline__ void xcd_barrier(const XcdBarrier& b) {
;     ...
;         const unsigned old = xb_add(&bar[XB_XSUB(b.x)], 1u);
;         const unsigned gen = old / nloc;
;         if (old + 1u == (gen + 1u) * nloc) {
;             __builtin_amdgcn_fence(__ATOMIC_RELEASE, "agent");
;             asm volatile("s_waitcnt vmcnt(0)" ::: "memory");
;             const unsigned og = xb_add(&bar[XB_TOP], 1u);
;             const unsigned tg = og / nx;
;             if (og + 1u == (tg + 1u) * nx) xb_add(&bar[XB_TOPGEN], 1u);
;             else XB_SPIN(xb_ld(&bar[XB_TOPGEN]) == tg, bar);
;             __builtin_amdgcn_fence(__ATOMIC_ACQUIRE, "agent");
;             xb_add(&bar[XB_XGEN(b.x)], 1u);
;             asm volatile("s_waitcnt vmcnt(0)" ::: "memory");
;         } else {
;             XB_SPIN(xb_ld(&bar[XB_XGEN(b.x)]) == gen, bar);
;             __builtin_amdgcn_fence(__ATOMIC_ACQUIRE, "agent");
;             asm volatile("s_waitcnt vmcnt(0)" ::: "memory");
.LBB0_243:
	s_or_b64 exec, exec, s[16:17]
	v_cvt_f32_u32_e32 v4, v2
	s_waitcnt vmcnt(0)
	v_readfirstlane_b32 s0, v3
	v_sub_u32_e32 v3, 0, v2
	v_rcp_iflag_f32_e32 v4, v4
	v_add_u32_e32 v5, s0, v1
	v_mul_f32_e32 v4, 0x4f7ffffe, v4
	v_cvt_u32_f32_e32 v4, v4
	v_mul_lo_u32 v1, v3, v4
	v_mul_hi_u32 v1, v4, v1
	v_add_u32_e32 v1, v4, v1
	v_mul_hi_u32 v1, v5, v1
	v_mul_lo_u32 v3, v1, v2
	v_sub_u32_e32 v3, v5, v3
	v_add_u32_e32 v4, 1, v1
	v_cmp_ge_u32_e32 vcc, v3, v2
	s_nop 1
	v_cndmask_b32_e32 v1, v1, v4, vcc
	v_sub_u32_e32 v4, v3, v2
	v_cndmask_b32_e32 v3, v3, v4, vcc
	v_add_u32_e32 v4, 1, v1
	v_cmp_ge_u32_e32 vcc, v3, v2
	v_add_u32_e32 v3, 1, v5
	s_nop 0
	v_cndmask_b32_e32 v1, v1, v4, vcc
	v_mul_lo_u32 v4, v2, v1
	v_add_u32_e32 v2, v4, v2
	v_cmp_ne_u32_e32 vcc, v3, v2
	s_and_saveexec_b64 s[0:1], vcc
	s_xor_b64 s[14:15], exec, s[0:1]
	s_cbranch_execz .LBB0_257
	s_waitcnt lgkmcnt(0)
	v_mov_b32_e32 v0, 0x83000
	global_load_dword v0, v0, s[10:11] offset:1280 sc1
	s_add_u32 s20, s10, 0x83500
	s_addc_u32 s21, s11, 0
	s_waitcnt vmcnt(0)
	v_cmp_eq_u32_e32 vcc, v0, v1
	s_and_saveexec_b64 s[16:17], vcc
	s_cbranch_execz .LBB0_256
	s_add_u32 s18, s10, 0x80200
	s_addc_u32 s19, s11, 0
	s_mov_b32 s0, 1
	s_mov_b64 s[22:23], 0
	v_mov_b32_e32 v0, 0
	s_branch .LBB0_247

; __device__ __forceinline__ unsigned xb_ld(unsigned* p)              { return __hip_atomic_load(p, __ATOMIC_RELAXED, __HIP_MEMORY_SCOPE_AGENT); }
; __device__ __forceinline__ unsigned xb_add(unsigned* p, unsigned v) { return __hip_atomic_fetch_add(p, v, __ATOMIC_RELAXED, __HIP_MEMORY_SCOPE_AGENT); }
; #define XB_SPIN(cond, bar) do { unsigned _sp = 0; while (cond) { __builtin_amdgcn_s_sleep(1); \
;     if ((++_sp & 255u) == 0u) { if (xb_ld(&(bar)[XB_TMO])) break; if (_sp > XB_SPIN_CAP) { atomicAdd(&(bar)[XB_TMO], 1u); break; } } } } while (0)
; __device__ __forceinline__ void xcd_barrier(const XcdBarrier& b) {
;     ...
;             __builtin_amdgcn_fence(__ATOMIC_RELEASE, "agent");
;             asm volatile("s_waitcnt vmcnt(0)" ::: "memory");
;             const unsigned og = xb_add(&bar[XB_TOP], 1u);
;             const unsigned tg = og / nx;
;             if (og + 1u == (tg + 1u) * nx) xb_add(&bar[XB_TOPGEN], 1u);
;             else XB_SPIN(xb_ld(&bar[XB_TOPGEN]) == tg, bar);
;             __builtin_amdgcn_fence(__ATOMIC_ACQUIRE, "agent");
;             xb_add(&bar[XB_XGEN(b.x)], 1u);
;             asm volatile("s_waitcnt vmcnt(0)" ::: "memory");
.LBB0_274:
	s_or_b64 exec, exec, s[10:11]
	s_mov_b64 s[10:11], exec
	v_mbcnt_lo_u32_b32 v0, s10, 0
	v_mbcnt_hi_u32_b32 v0, s11, v0
	v_cmp_eq_u32_e32 vcc, 0, v0
	s_waitcnt vmcnt(0)
	buffer_inv sc1
	s_and_saveexec_b64 s[14:15], vcc
	s_cbranch_execz .LBB0_276
	s_bcnt1_i32_b64 s0, s[10:11]
	v_mov_b32_e32 v0, 0x2000
	v_mov_b32_e32 v1, s0
.LBB0_276:
	s_or_b64 exec, exec, s[14:15]
	s_waitcnt vmcnt(0)

; __device__ __forceinline__ unsigned xb_ld(unsigned* p)              { return __hip_atomic_load(p, __ATOMIC_RELAXED, __HIP_MEMORY_SCOPE_AGENT); }
; __device__ __forceinline__ unsigned xb_add(unsigned* p, unsigned v) { return __hip_atomic_fetch_add(p, v, __ATOMIC_RELAXED, __HIP_MEMORY_SCOPE_AGENT); }
; #define XB_SPIN(cond, bar) do { unsigned _sp = 0; while (cond) { __builtin_amdgcn_s_sleep(1); \
;     if ((++_sp & 255u) == 0u) { if (xb_ld(&(bar)[XB_TMO])) break; if (_sp > XB_SPIN_CAP) { atomicAdd(&(bar)[XB_TMO], 1u); break; } } } } while (0)
; __device__ __forceinline__ void xcd_barrier(const XcdBarrier& b) {
;     ...
;         const unsigned old = xb_add(&bar[XB_XSUB(b.x)], 1u);
;         const unsigned gen = old / nloc;
;         if (old + 1u == (gen + 1u) * nloc) {
;             __builtin_amdgcn_fence(__ATOMIC_RELEASE, "agent");
;             asm volatile("s_waitcnt vmcnt(0)" ::: "memory");
;             const unsigned og = xb_add(&bar[XB_TOP], 1u);
;             const unsigned tg = og / nx;
;             if (og + 1u == (tg + 1u) * nx) xb_add(&bar[XB_TOPGEN], 1u);
;             else XB_SPIN(xb_ld(&bar[XB_TOPGEN]) == tg, bar);
;             __builtin_amdgcn_fence(__ATOMIC_ACQUIRE, "agent");
;             xb_add(&bar[XB_XGEN(b.x)], 1u);
;             asm volatile("s_waitcnt vmcnt(0)" ::: "memory");
;         } else {
;             XB_SPIN(xb_ld(&bar[XB_XGEN(b.x)]) == gen, bar);
;             __builtin_amdgcn_fence(__ATOMIC_ACQUIRE, "agent");
;             asm volatile("s_waitcnt vmcnt(0)" ::: "memory");
.LBB0_341:
	s_or_b64 exec, exec, s[18:19]
	v_cvt_f32_u32_e32 v4, v2
	s_waitcnt vmcnt(0)
	v_readfirstlane_b32 s0, v3
	v_sub_u32_e32 v3, 0, v2
	v_rcp_iflag_f32_e32 v4, v4
	v_add_u32_e32 v5, s0, v1
	v_mul_f32_e32 v4, 0x4f7ffffe, v4
	v_cvt_u32_f32_e32 v4, v4
	v_mul_lo_u32 v1, v3, v4
	v_mul_hi_u32 v1, v4, v1
	v_add_u32_e32 v1, v4, v1
	v_mul_hi_u32 v1, v5, v1
	v_mul_lo_u32 v3, v1, v2
	v_sub_u32_e32 v3, v5, v3
	v_add_u32_e32 v4, 1, v1
	v_cmp_ge_u32_e32 vcc, v3, v2
	s_nop 1
	v_cndmask_b32_e32 v1, v1, v4, vcc
	v_sub_u32_e32 v4, v3, v2
	v_cndmask_b32_e32 v3, v3, v4, vcc
	v_add_u32_e32 v4, 1, v1
	v_cmp_ge_u32_e32 vcc, v3, v2
	v_add_u32_e32 v3, 1, v5
	s_nop 0
	v_cndmask_b32_e32 v1, v1, v4, vcc
	v_mul_lo_u32 v4, v2, v1
	v_add_u32_e32 v2, v4, v2
	v_cmp_ne_u32_e32 vcc, v3, v2
	s_and_saveexec_b64 s[0:1], vcc
	s_xor_b64 s[16:17], exec, s[0:1]
	s_cbranch_execz .LBB0_355
	s_waitcnt lgkmcnt(0)
	v_mov_b32_e32 v0, 0x83000
	global_load_dword v0, v0, s[12:13] offset:1280 sc1
	s_add_u32 s22, s12, 0x83500
	s_addc_u32 s23, s13, 0
	s_waitcnt vmcnt(0)
	v_cmp_eq_u32_e32 vcc, v0, v1
	s_and_saveexec_b64 s[18:19], vcc
	s_cbranch_execz .LBB0_354
	s_add_u32 s20, s12, 0x80200
	s_addc_u32 s21, s13, 0
	s_mov_b32 s0, 1
	s_mov_b64 s[24:25], 0
	v_mov_b32_e32 v0, 0
	s_branch .LBB0_345

; __device__ __forceinline__ unsigned xb_ld(unsigned* p)              { return __hip_atomic_load(p, __ATOMIC_RELAXED, __HIP_MEMORY_SCOPE_AGENT); }
; __device__ __forceinline__ unsigned xb_add(unsigned* p, unsigned v) { return __hip_atomic_fetch_add(p, v, __ATOMIC_RELAXED, __HIP_MEMORY_SCOPE_AGENT); }
; #define XB_SPIN(cond, bar) do { unsigned _sp = 0; while (cond) { __builtin_amdgcn_s_sleep(1); \
;     if ((++_sp & 255u) == 0u) { if (xb_ld(&(bar)[XB_TMO])) break; if (_sp > XB_SPIN_CAP) { atomicAdd(&(bar)[XB_TMO], 1u); break; } } } } while (0)
; __device__ __forceinline__ void xcd_barrier(const XcdBarrier& b) {
;     ...
;             __builtin_amdgcn_fence(__ATOMIC_RELEASE, "agent");
;             asm volatile("s_waitcnt vmcnt(0)" ::: "memory");
;             const unsigned og = xb_add(&bar[XB_TOP], 1u);
;             const unsigned tg = og / nx;
;             if (og + 1u == (tg + 1u) * nx) xb_add(&bar[XB_TOPGEN], 1u);
;             else XB_SPIN(xb_ld(&bar[XB_TOPGEN]) == tg, bar);
;             __builtin_amdgcn_fence(__ATOMIC_ACQUIRE, "agent");
;             xb_add(&bar[XB_XGEN(b.x)], 1u);
;             asm volatile("s_waitcnt vmcnt(0)" ::: "memory");
.LBB0_372:
	s_or_b64 exec, exec, s[12:13]
	s_mov_b64 s[12:13], exec
	v_mbcnt_lo_u32_b32 v0, s12, 0
	v_mbcnt_hi_u32_b32 v0, s13, v0
	v_cmp_eq_u32_e32 vcc, 0, v0
	s_waitcnt vmcnt(0)
	buffer_inv sc1
	s_and_saveexec_b64 s[16:17], vcc
	s_cbranch_execz .LBB0_374
	s_bcnt1_i32_b64 s0, s[12:13]
	v_mov_b32_e32 v0, 0x2000
	v_mov_b32_e32 v1, s0
.LBB0_374:
	s_or_b64 exec, exec, s[16:17]
	s_waitcnt vmcnt(0)

; __device__ __forceinline__ unsigned xb_ld(unsigned* p)              { return __hip_atomic_load(p, __ATOMIC_RELAXED, __HIP_MEMORY_SCOPE_AGENT); }
; __device__ __forceinline__ unsigned xb_add(unsigned* p, unsigned v) { return __hip_atomic_fetch_add(p, v, __ATOMIC_RELAXED, __HIP_MEMORY_SCOPE_AGENT); }
; #define XB_SPIN(cond, bar) do { unsigned _sp = 0; while (cond) { __builtin_amdgcn_s_sleep(1); \
;     if ((++_sp & 255u) == 0u) { if (xb_ld(&(bar)[XB_TMO])) break; if (_sp > XB_SPIN_CAP) { atomicAdd(&(bar)[XB_TMO], 1u); break; } } } } while (0)
; __device__ __forceinline__ void xcd_barrier(const XcdBarrier& b) {
;     ...
;             __builtin_amdgcn_fence(__ATOMIC_RELEASE, "agent");
;             asm volatile("s_waitcnt vmcnt(0)" ::: "memory");
;             const unsigned og = xb_add(&bar[XB_TOP], 1u);
;             const unsigned tg = og / nx;
;             if (og + 1u == (tg + 1u) * nx) xb_add(&bar[XB_TOPGEN], 1u);
;             else XB_SPIN(xb_ld(&bar[XB_TOPGEN]) == tg, bar);
;             __builtin_amdgcn_fence(__ATOMIC_ACQUIRE, "agent");
;             xb_add(&bar[XB_XGEN(b.x)], 1u);
;             asm volatile("s_waitcnt vmcnt(0)" ::: "memory");
.LBB0_588:
	s_or_b64 exec, exec, s[12:13]
	s_mov_b64 s[12:13], exec
	v_mbcnt_lo_u32_b32 v0, s12, 0
	v_mbcnt_hi_u32_b32 v0, s13, v0
	v_cmp_eq_u32_e32 vcc, 0, v0
	s_waitcnt vmcnt(0)
	buffer_inv sc1
	s_and_saveexec_b64 s[16:17], vcc
	s_cbranch_execz .LBB0_590
	s_bcnt1_i32_b64 s0, s[12:13]
	v_mov_b32_e32 v0, 0x2000
	v_mov_b32_e32 v1, s0
.LBB0_590:
	s_or_b64 exec, exec, s[16:17]
	s_waitcnt vmcnt(0)

; __device__ __forceinline__ unsigned xb_ld(unsigned* p)              { return __hip_atomic_load(p, __ATOMIC_RELAXED, __HIP_MEMORY_SCOPE_AGENT); }
; __device__ __forceinline__ unsigned xb_add(unsigned* p, unsigned v) { return __hip_atomic_fetch_add(p, v, __ATOMIC_RELAXED, __HIP_MEMORY_SCOPE_AGENT); }
; #define XB_SPIN(cond, bar) do { unsigned _sp = 0; while (cond) { __builtin_amdgcn_s_sleep(1); \
;     if ((++_sp & 255u) == 0u) { if (xb_ld(&(bar)[XB_TMO])) break; if (_sp > XB_SPIN_CAP) { atomicAdd(&(bar)[XB_TMO], 1u); break; } } } } while (0)
; __device__ __forceinline__ void xcd_barrier(const XcdBarrier& b) {
;     ...
;         const unsigned old = xb_add(&bar[XB_XSUB(b.x)], 1u);
;         const unsigned gen = old / nloc;
;         if (old + 1u == (gen + 1u) * nloc) {
;             __builtin_amdgcn_fence(__ATOMIC_RELEASE, "agent");
;             asm volatile("s_waitcnt vmcnt(0)" ::: "memory");
;             const unsigned og = xb_add(&bar[XB_TOP], 1u);
;             const unsigned tg = og / nx;
;             if (og + 1u == (tg + 1u) * nx) xb_add(&bar[XB_TOPGEN], 1u);
;             else XB_SPIN(xb_ld(&bar[XB_TOPGEN]) == tg, bar);
;             __builtin_amdgcn_fence(__ATOMIC_ACQUIRE, "agent");
;             xb_add(&bar[XB_XGEN(b.x)], 1u);
;             asm volatile("s_waitcnt vmcnt(0)" ::: "memory");
;         } else {
;             XB_SPIN(xb_ld(&bar[XB_XGEN(b.x)]) == gen, bar);
;             __builtin_amdgcn_fence(__ATOMIC_ACQUIRE, "agent");
;             asm volatile("s_waitcnt vmcnt(0)" ::: "memory");
.LBB0_675:
	s_or_b64 exec, exec, s[20:21]
	v_cvt_f32_u32_e32 v4, v2
	s_waitcnt vmcnt(0)
	v_readfirstlane_b32 s0, v3
	v_sub_u32_e32 v3, 0, v2
	v_rcp_iflag_f32_e32 v4, v4
	v_add_u32_e32 v5, s0, v1
	v_mul_f32_e32 v4, 0x4f7ffffe, v4
	v_cvt_u32_f32_e32 v4, v4
	v_mul_lo_u32 v1, v3, v4
	v_mul_hi_u32 v1, v4, v1
	v_add_u32_e32 v1, v4, v1
	v_mul_hi_u32 v1, v5, v1
	v_mul_lo_u32 v3, v1, v2
	v_sub_u32_e32 v3, v5, v3
	v_add_u32_e32 v4, 1, v1
	v_cmp_ge_u32_e32 vcc, v3, v2
	s_nop 1
	v_cndmask_b32_e32 v1, v1, v4, vcc
	v_sub_u32_e32 v4, v3, v2
	v_cndmask_b32_e32 v3, v3, v4, vcc
	v_add_u32_e32 v4, 1, v1
	v_cmp_ge_u32_e32 vcc, v3, v2
	v_add_u32_e32 v3, 1, v5
	s_nop 0
	v_cndmask_b32_e32 v1, v1, v4, vcc
	v_mul_lo_u32 v4, v2, v1
	v_add_u32_e32 v2, v4, v2
	v_cmp_ne_u32_e32 vcc, v3, v2
	s_and_saveexec_b64 s[0:1], vcc
	s_xor_b64 s[18:19], exec, s[0:1]
	s_cbranch_execz .LBB0_689
	s_waitcnt lgkmcnt(0)
	v_mov_b32_e32 v0, 0x83000
	global_load_dword v0, v0, s[14:15] offset:1280 sc1
	s_add_u32 s24, s14, 0x83500
	s_addc_u32 s25, s15, 0
	s_waitcnt vmcnt(0)
	v_cmp_eq_u32_e32 vcc, v0, v1
	s_and_saveexec_b64 s[20:21], vcc
	s_cbranch_execz .LBB0_688
	s_add_u32 s22, s14, 0x80200
	s_addc_u32 s23, s15, 0
	s_mov_b32 s0, 1
	s_mov_b64 s[26:27], 0
	v_mov_b32_e32 v0, 0
	s_branch .LBB0_679

; __device__ __forceinline__ unsigned xb_ld(unsigned* p)              { return __hip_atomic_load(p, __ATOMIC_RELAXED, __HIP_MEMORY_SCOPE_AGENT); }
; __device__ __forceinline__ unsigned xb_add(unsigned* p, unsigned v) { return __hip_atomic_fetch_add(p, v, __ATOMIC_RELAXED, __HIP_MEMORY_SCOPE_AGENT); }
; #define XB_SPIN(cond, bar) do { unsigned _sp = 0; while (cond) { __builtin_amdgcn_s_sleep(1); \
;     if ((++_sp & 255u) == 0u) { if (xb_ld(&(bar)[XB_TMO])) break; if (_sp > XB_SPIN_CAP) { atomicAdd(&(bar)[XB_TMO], 1u); break; } } } } while (0)
; __device__ __forceinline__ void xcd_barrier(const XcdBarrier& b) {
;     ...
;             __builtin_amdgcn_fence(__ATOMIC_RELEASE, "agent");
;             asm volatile("s_waitcnt vmcnt(0)" ::: "memory");
;             const unsigned og = xb_add(&bar[XB_TOP], 1u);
;             const unsigned tg = og / nx;
;             if (og + 1u == (tg + 1u) * nx) xb_add(&bar[XB_TOPGEN], 1u);
;             else XB_SPIN(xb_ld(&bar[XB_TOPGEN]) == tg, bar);
;             __builtin_amdgcn_fence(__ATOMIC_ACQUIRE, "agent");
;             xb_add(&bar[XB_XGEN(b.x)], 1u);
;             asm volatile("s_waitcnt vmcnt(0)" ::: "memory");
.LBB0_706:
	s_or_b64 exec, exec, s[14:15]
	s_mov_b64 s[14:15], exec
	v_mbcnt_lo_u32_b32 v0, s14, 0
	v_mbcnt_hi_u32_b32 v0, s15, v0
	v_cmp_eq_u32_e32 vcc, 0, v0
	s_waitcnt vmcnt(0)
	buffer_inv sc1
	s_and_saveexec_b64 s[18:19], vcc
	s_cbranch_execz .LBB0_708
	s_bcnt1_i32_b64 s0, s[14:15]
	v_mov_b32_e32 v0, 0x2000
	v_mov_b32_e32 v1, s0
.LBB0_708:
	s_or_b64 exec, exec, s[18:19]
	s_waitcnt vmcnt(0)

; __device__ __forceinline__ unsigned xb_ld(unsigned* p)              { return __hip_atomic_load(p, __ATOMIC_RELAXED, __HIP_MEMORY_SCOPE_AGENT); }
; __device__ __forceinline__ unsigned xb_add(unsigned* p, unsigned v) { return __hip_atomic_fetch_add(p, v, __ATOMIC_RELAXED, __HIP_MEMORY_SCOPE_AGENT); }
; #define XB_SPIN(cond, bar) do { unsigned _sp = 0; while (cond) { __builtin_amdgcn_s_sleep(1); \
;     if ((++_sp & 255u) == 0u) { if (xb_ld(&(bar)[XB_TMO])) break; if (_sp > XB_SPIN_CAP) { atomicAdd(&(bar)[XB_TMO], 1u); break; } } } } while (0)
; __device__ __forceinline__ void xcd_barrier(const XcdBarrier& b) {
;     ...
;         const unsigned old = xb_add(&bar[XB_XSUB(b.x)], 1u);
;         const unsigned gen = old / nloc;
;         if (old + 1u == (gen + 1u) * nloc) {
;             __builtin_amdgcn_fence(__ATOMIC_RELEASE, "agent");
;             asm volatile("s_waitcnt vmcnt(0)" ::: "memory");
;             const unsigned og = xb_add(&bar[XB_TOP], 1u);
;             const unsigned tg = og / nx;
;             if (og + 1u == (tg + 1u) * nx) xb_add(&bar[XB_TOPGEN], 1u);
;             else XB_SPIN(xb_ld(&bar[XB_TOPGEN]) == tg, bar);
;             __builtin_amdgcn_fence(__ATOMIC_ACQUIRE, "agent");
;             xb_add(&bar[XB_XGEN(b.x)], 1u);
;             asm volatile("s_waitcnt vmcnt(0)" ::: "memory");
;         } else {
;             XB_SPIN(xb_ld(&bar[XB_XGEN(b.x)]) == gen, bar);
;             __builtin_amdgcn_fence(__ATOMIC_ACQUIRE, "agent");
;             asm volatile("s_waitcnt vmcnt(0)" ::: "memory");
.LBB0_778:
	s_or_b64 exec, exec, s[20:21]
	v_cvt_f32_u32_e32 v4, v2
	s_waitcnt vmcnt(0)
	v_readfirstlane_b32 s0, v3
	v_sub_u32_e32 v3, 0, v2
	v_rcp_iflag_f32_e32 v4, v4
	v_add_u32_e32 v5, s0, v1
	v_mul_f32_e32 v4, 0x4f7ffffe, v4
	v_cvt_u32_f32_e32 v4, v4
	v_mul_lo_u32 v1, v3, v4
	v_mul_hi_u32 v1, v4, v1
	v_add_u32_e32 v1, v4, v1
	v_mul_hi_u32 v1, v5, v1
	v_mul_lo_u32 v3, v1, v2
	v_sub_u32_e32 v3, v5, v3
	v_add_u32_e32 v4, 1, v1
	v_cmp_ge_u32_e32 vcc, v3, v2
	s_nop 1
	v_cndmask_b32_e32 v1, v1, v4, vcc
	v_sub_u32_e32 v4, v3, v2
	v_cndmask_b32_e32 v3, v3, v4, vcc
	v_add_u32_e32 v4, 1, v1
	v_cmp_ge_u32_e32 vcc, v3, v2
	v_add_u32_e32 v3, 1, v5
	s_nop 0
	v_cndmask_b32_e32 v1, v1, v4, vcc
	v_mul_lo_u32 v4, v2, v1
	v_add_u32_e32 v2, v4, v2
	v_cmp_ne_u32_e32 vcc, v3, v2
	s_and_saveexec_b64 s[0:1], vcc
	s_xor_b64 s[18:19], exec, s[0:1]
	s_cbranch_execz .LBB0_792
	s_waitcnt lgkmcnt(0)
	v_mov_b32_e32 v0, 0x83000
	global_load_dword v0, v0, s[12:13] offset:1280 sc1
	s_add_u32 s24, s12, 0x83500
	s_addc_u32 s25, s13, 0
	s_waitcnt vmcnt(0)
	v_cmp_eq_u32_e32 vcc, v0, v1
	s_and_saveexec_b64 s[20:21], vcc
	s_cbranch_execz .LBB0_791
	s_add_u32 s22, s12, 0x80200
	s_addc_u32 s23, s13, 0
	s_mov_b32 s0, 1
	s_mov_b64 s[26:27], 0
	v_mov_b32_e32 v0, 0
	s_branch .LBB0_782

; __device__ __forceinline__ unsigned xb_ld(unsigned* p)              { return __hip_atomic_load(p, __ATOMIC_RELAXED, __HIP_MEMORY_SCOPE_AGENT); }
; __device__ __forceinline__ unsigned xb_add(unsigned* p, unsigned v) { return __hip_atomic_fetch_add(p, v, __ATOMIC_RELAXED, __HIP_MEMORY_SCOPE_AGENT); }
; #define XB_SPIN(cond, bar) do { unsigned _sp = 0; while (cond) { __builtin_amdgcn_s_sleep(1); \
;     if ((++_sp & 255u) == 0u) { if (xb_ld(&(bar)[XB_TMO])) break; if (_sp > XB_SPIN_CAP) { atomicAdd(&(bar)[XB_TMO], 1u); break; } } } } while (0)
; __device__ __forceinline__ void xcd_barrier(const XcdBarrier& b) {
;     ...
;             __builtin_amdgcn_fence(__ATOMIC_RELEASE, "agent");
;             asm volatile("s_waitcnt vmcnt(0)" ::: "memory");
;             const unsigned og = xb_add(&bar[XB_TOP], 1u);
;             const unsigned tg = og / nx;
;             if (og + 1u == (tg + 1u) * nx) xb_add(&bar[XB_TOPGEN], 1u);
;             else XB_SPIN(xb_ld(&bar[XB_TOPGEN]) == tg, bar);
;             __builtin_amdgcn_fence(__ATOMIC_ACQUIRE, "agent");
;             xb_add(&bar[XB_XGEN(b.x)], 1u);
;             asm volatile("s_waitcnt vmcnt(0)" ::: "memory");
.LBB0_809:
	s_or_b64 exec, exec, s[12:13]
	s_mov_b64 s[12:13], exec
	v_mbcnt_lo_u32_b32 v0, s12, 0
	v_mbcnt_hi_u32_b32 v0, s13, v0
	v_cmp_eq_u32_e32 vcc, 0, v0
	s_waitcnt vmcnt(0)
	buffer_inv sc1
	s_and_saveexec_b64 s[18:19], vcc
	s_cbranch_execz .LBB0_811
	s_bcnt1_i32_b64 s0, s[12:13]
	v_mov_b32_e32 v0, 0x2000
	v_mov_b32_e32 v1, s0
.LBB0_811:
	s_or_b64 exec, exec, s[18:19]
	s_waitcnt vmcnt(0)

; __device__ __forceinline__ unsigned xb_ld(unsigned* p)              { return __hip_atomic_load(p, __ATOMIC_RELAXED, __HIP_MEMORY_SCOPE_AGENT); }
; __device__ __forceinline__ unsigned xb_add(unsigned* p, unsigned v) { return __hip_atomic_fetch_add(p, v, __ATOMIC_RELAXED, __HIP_MEMORY_SCOPE_AGENT); }
; #define XB_SPIN(cond, bar) do { unsigned _sp = 0; while (cond) { __builtin_amdgcn_s_sleep(1); \
;     if ((++_sp & 255u) == 0u) { if (xb_ld(&(bar)[XB_TMO])) break; if (_sp > XB_SPIN_CAP) { atomicAdd(&(bar)[XB_TMO], 1u); break; } } } } while (0)
; __device__ __forceinline__ void xcd_barrier(const XcdBarrier& b) {
;     ...
;             __builtin_amdgcn_fence(__ATOMIC_RELEASE, "agent");
;             asm volatile("s_waitcnt vmcnt(0)" ::: "memory");
;             const unsigned og = xb_add(&bar[XB_TOP], 1u);
;             const unsigned tg = og / nx;
;             if (og + 1u == (tg + 1u) * nx) xb_add(&bar[XB_TOPGEN], 1u);
;             else XB_SPIN(xb_ld(&bar[XB_TOPGEN]) == tg, bar);
;             __builtin_amdgcn_fence(__ATOMIC_ACQUIRE, "agent");
;             xb_add(&bar[XB_XGEN(b.x)], 1u);
;             asm volatile("s_waitcnt vmcnt(0)" ::: "memory");
.LBB0_1214:
	s_or_b64 exec, exec, s[10:11]
	s_mov_b64 s[10:11], exec
	v_mbcnt_lo_u32_b32 v0, s10, 0
	v_mbcnt_hi_u32_b32 v0, s11, v0
	v_cmp_eq_u32_e32 vcc, 0, v0
	s_waitcnt vmcnt(0)
	buffer_inv sc1
	s_and_saveexec_b64 s[14:15], vcc
	s_cbranch_execz .LBB0_1216
	s_bcnt1_i32_b64 s0, s[10:11]
	v_mov_b32_e32 v0, 0x2000
	v_mov_b32_e32 v1, s0
.LBB0_1216:
	s_or_b64 exec, exec, s[14:15]
	s_waitcnt vmcnt(0)

; __device__ __forceinline__ unsigned xb_ld(unsigned* p)              { return __hip_atomic_load(p, __ATOMIC_RELAXED, __HIP_MEMORY_SCOPE_AGENT); }
; __device__ __forceinline__ unsigned xb_add(unsigned* p, unsigned v) { return __hip_atomic_fetch_add(p, v, __ATOMIC_RELAXED, __HIP_MEMORY_SCOPE_AGENT); }
; #define XB_SPIN(cond, bar) do { unsigned _sp = 0; while (cond) { __builtin_amdgcn_s_sleep(1); \
;     if ((++_sp & 255u) == 0u) { if (xb_ld(&(bar)[XB_TMO])) break; if (_sp > XB_SPIN_CAP) { atomicAdd(&(bar)[XB_TMO], 1u); break; } } } } while (0)
; __device__ __forceinline__ void xcd_barrier(const XcdBarrier& b) {
;     ...
;         const unsigned old = xb_add(&bar[XB_XSUB(b.x)], 1u);
;         const unsigned gen = old / nloc;
;         if (old + 1u == (gen + 1u) * nloc) {
;             __builtin_amdgcn_fence(__ATOMIC_RELEASE, "agent");
;             asm volatile("s_waitcnt vmcnt(0)" ::: "memory");
;             const unsigned og = xb_add(&bar[XB_TOP], 1u);
;             const unsigned tg = og / nx;
;             if (og + 1u == (tg + 1u) * nx) xb_add(&bar[XB_TOPGEN], 1u);
;             else XB_SPIN(xb_ld(&bar[XB_TOPGEN]) == tg, bar);
;             __builtin_amdgcn_fence(__ATOMIC_ACQUIRE, "agent");
;             xb_add(&bar[XB_XGEN(b.x)], 1u);
;             asm volatile("s_waitcnt vmcnt(0)" ::: "memory");
;         } else {
;             XB_SPIN(xb_ld(&bar[XB_XGEN(b.x)]) == gen, bar);
;             __builtin_amdgcn_fence(__ATOMIC_ACQUIRE, "agent");
;             asm volatile("s_waitcnt vmcnt(0)" ::: "memory");
.LBB0_1478:
	s_or_b64 exec, exec, s[14:15]
	v_cvt_f32_u32_e32 v4, v2
	s_waitcnt vmcnt(0)
	v_readfirstlane_b32 s0, v3
	v_sub_u32_e32 v3, 0, v2
	v_rcp_iflag_f32_e32 v4, v4
	v_add_u32_e32 v5, s0, v1
	v_mul_f32_e32 v4, 0x4f7ffffe, v4
	v_cvt_u32_f32_e32 v4, v4
	v_mul_lo_u32 v1, v3, v4
	v_mul_hi_u32 v1, v4, v1
	v_add_u32_e32 v1, v4, v1
	v_mul_hi_u32 v1, v5, v1
	v_mul_lo_u32 v3, v1, v2
	v_sub_u32_e32 v3, v5, v3
	v_add_u32_e32 v4, 1, v1
	v_cmp_ge_u32_e32 vcc, v3, v2
	s_nop 1
	v_cndmask_b32_e32 v1, v1, v4, vcc
	v_sub_u32_e32 v4, v3, v2
	v_cndmask_b32_e32 v3, v3, v4, vcc
	v_add_u32_e32 v4, 1, v1
	v_cmp_ge_u32_e32 vcc, v3, v2
	v_add_u32_e32 v3, 1, v5
	s_nop 0
	v_cndmask_b32_e32 v1, v1, v4, vcc
	v_mul_lo_u32 v4, v2, v1
	v_add_u32_e32 v2, v4, v2
	v_cmp_ne_u32_e32 vcc, v3, v2
	s_and_saveexec_b64 s[0:1], vcc
	s_xor_b64 s[12:13], exec, s[0:1]
	s_cbranch_execz .LBB0_1492
	s_waitcnt lgkmcnt(0)
	v_mov_b32_e32 v0, 0x83000
	global_load_dword v0, v0, s[8:9] offset:1280 sc1
	s_add_u32 s18, s8, 0x83500
	s_addc_u32 s19, s9, 0
	s_waitcnt vmcnt(0)
	v_cmp_eq_u32_e32 vcc, v0, v1
	s_and_saveexec_b64 s[14:15], vcc
	s_cbranch_execz .LBB0_1491
	s_add_u32 s16, s8, 0x80200
	s_addc_u32 s17, s9, 0
	s_mov_b32 s0, 1
	s_mov_b64 s[20:21], 0
	v_mov_b32_e32 v0, 0
	s_branch .LBB0_1482

; __device__ __forceinline__ unsigned xb_ld(unsigned* p)              { return __hip_atomic_load(p, __ATOMIC_RELAXED, __HIP_MEMORY_SCOPE_AGENT); }
; __device__ __forceinline__ unsigned xb_add(unsigned* p, unsigned v) { return __hip_atomic_fetch_add(p, v, __ATOMIC_RELAXED, __HIP_MEMORY_SCOPE_AGENT); }
; #define XB_SPIN(cond, bar) do { unsigned _sp = 0; while (cond) { __builtin_amdgcn_s_sleep(1); \
;     if ((++_sp & 255u) == 0u) { if (xb_ld(&(bar)[XB_TMO])) break; if (_sp > XB_SPIN_CAP) { atomicAdd(&(bar)[XB_TMO], 1u); break; } } } } while (0)
; __device__ __forceinline__ void xcd_barrier(const XcdBarrier& b) {
;     ...
;             __builtin_amdgcn_fence(__ATOMIC_RELEASE, "agent");
;             asm volatile("s_waitcnt vmcnt(0)" ::: "memory");
;             const unsigned og = xb_add(&bar[XB_TOP], 1u);
;             const unsigned tg = og / nx;
;             if (og + 1u == (tg + 1u) * nx) xb_add(&bar[XB_TOPGEN], 1u);
;             else XB_SPIN(xb_ld(&bar[XB_TOPGEN]) == tg, bar);
;             __builtin_amdgcn_fence(__ATOMIC_ACQUIRE, "agent");
;             xb_add(&bar[XB_XGEN(b.x)], 1u);
;             asm volatile("s_waitcnt vmcnt(0)" ::: "memory");
.LBB0_1509:
	s_or_b64 exec, exec, s[8:9]
	s_mov_b64 s[8:9], exec
	v_mbcnt_lo_u32_b32 v0, s8, 0
	v_mbcnt_hi_u32_b32 v0, s9, v0
	v_cmp_eq_u32_e32 vcc, 0, v0
	s_waitcnt vmcnt(0)
	buffer_inv sc1
	s_and_saveexec_b64 s[12:13], vcc
	s_cbranch_execz .LBB0_1511
	s_bcnt1_i32_b64 s0, s[8:9]
	v_mov_b32_e32 v0, 0x2000
	v_mov_b32_e32 v1, s0
.LBB0_1511:
	s_or_b64 exec, exec, s[12:13]
	s_waitcnt vmcnt(0)

; __device__ __forceinline__ unsigned xb_ld(unsigned* p)              { return __hip_atomic_load(p, __ATOMIC_RELAXED, __HIP_MEMORY_SCOPE_AGENT); }
; __device__ __forceinline__ unsigned xb_add(unsigned* p, unsigned v) { return __hip_atomic_fetch_add(p, v, __ATOMIC_RELAXED, __HIP_MEMORY_SCOPE_AGENT); }
; #define XB_SPIN(cond, bar) do { unsigned _sp = 0; while (cond) { __builtin_amdgcn_s_sleep(1); \
;     if ((++_sp & 255u) == 0u) { if (xb_ld(&(bar)[XB_TMO])) break; if (_sp > XB_SPIN_CAP) { atomicAdd(&(bar)[XB_TMO], 1u); break; } } } } while (0)
; __device__ __forceinline__ void xcd_barrier(const XcdBarrier& b) {
;     ...
;             __builtin_amdgcn_fence(__ATOMIC_RELEASE, "agent");
;             asm volatile("s_waitcnt vmcnt(0)" ::: "memory");
;             const unsigned og = xb_add(&bar[XB_TOP], 1u);
;             const unsigned tg = og / nx;
;             if (og + 1u == (tg + 1u) * nx) xb_add(&bar[XB_TOPGEN], 1u);
;             else XB_SPIN(xb_ld(&bar[XB_TOPGEN]) == tg, bar);
;             __builtin_amdgcn_fence(__ATOMIC_ACQUIRE, "agent");
;             xb_add(&bar[XB_XGEN(b.x)], 1u);
;             asm volatile("s_waitcnt vmcnt(0)" ::: "memory");
.LBB0_1632:
	s_or_b64 exec, exec, s[8:9]
	s_mov_b64 s[8:9], exec
	v_mbcnt_lo_u32_b32 v0, s8, 0
	v_mbcnt_hi_u32_b32 v0, s9, v0
	v_cmp_eq_u32_e32 vcc, 0, v0
	s_waitcnt vmcnt(0)
	buffer_inv sc1
	s_and_saveexec_b64 s[12:13], vcc
	s_cbranch_execz .LBB0_1634
	s_bcnt1_i32_b64 s0, s[8:9]
	v_mov_b32_e32 v0, 0x2000
	v_mov_b32_e32 v1, s0
.LBB0_1634:
	s_or_b64 exec, exec, s[12:13]
	s_waitcnt vmcnt(0)

; __device__ __forceinline__ unsigned xb_ld(unsigned* p)              { return __hip_atomic_load(p, __ATOMIC_RELAXED, __HIP_MEMORY_SCOPE_AGENT); }
; __device__ __forceinline__ unsigned xb_add(unsigned* p, unsigned v) { return __hip_atomic_fetch_add(p, v, __ATOMIC_RELAXED, __HIP_MEMORY_SCOPE_AGENT); }
; #define XB_SPIN(cond, bar) do { unsigned _sp = 0; while (cond) { __builtin_amdgcn_s_sleep(1); \
;     if ((++_sp & 255u) == 0u) { if (xb_ld(&(bar)[XB_TMO])) break; if (_sp > XB_SPIN_CAP) { atomicAdd(&(bar)[XB_TMO], 1u); break; } } } } while (0)
; __device__ __forceinline__ void xcd_barrier(const XcdBarrier& b) {
;     ...
;             __builtin_amdgcn_fence(__ATOMIC_RELEASE, "agent");
;             asm volatile("s_waitcnt vmcnt(0)" ::: "memory");
;             const unsigned og = xb_add(&bar[XB_TOP], 1u);
;             const unsigned tg = og / nx;
;             if (og + 1u == (tg + 1u) * nx) xb_add(&bar[XB_TOPGEN], 1u);
;             else XB_SPIN(xb_ld(&bar[XB_TOPGEN]) == tg, bar);
;             __builtin_amdgcn_fence(__ATOMIC_ACQUIRE, "agent");
;             xb_add(&bar[XB_XGEN(b.x)], 1u);
;             asm volatile("s_waitcnt vmcnt(0)" ::: "memory");
.LBB0_1726:
	s_or_b64 exec, exec, s[8:9]
	s_mov_b64 s[8:9], exec
	v_mbcnt_lo_u32_b32 v0, s8, 0
	v_mbcnt_hi_u32_b32 v0, s9, v0
	v_cmp_eq_u32_e32 vcc, 0, v0
	s_waitcnt vmcnt(0)
	buffer_inv sc1
	s_and_saveexec_b64 s[12:13], vcc
	s_cbranch_execz .LBB0_1728
	s_bcnt1_i32_b64 s0, s[8:9]
	v_mov_b32_e32 v0, 0x2000
	v_mov_b32_e32 v1, s0
.LBB0_1728:
	s_or_b64 exec, exec, s[12:13]
	s_waitcnt vmcnt(0)

; __device__ __forceinline__ unsigned xb_ld(unsigned* p)              { return __hip_atomic_load(p, __ATOMIC_RELAXED, __HIP_MEMORY_SCOPE_AGENT); }
; __device__ __forceinline__ unsigned xb_add(unsigned* p, unsigned v) { return __hip_atomic_fetch_add(p, v, __ATOMIC_RELAXED, __HIP_MEMORY_SCOPE_AGENT); }
; #define XB_SPIN(cond, bar) do { unsigned _sp = 0; while (cond) { __builtin_amdgcn_s_sleep(1); \
;     if ((++_sp & 255u) == 0u) { if (xb_ld(&(bar)[XB_TMO])) break; if (_sp > XB_SPIN_CAP) { atomicAdd(&(bar)[XB_TMO], 1u); break; } } } } while (0)
; __device__ __forceinline__ void xcd_barrier(const XcdBarrier& b) {
;     ...
;             __builtin_amdgcn_fence(__ATOMIC_RELEASE, "agent");
;             asm volatile("s_waitcnt vmcnt(0)" ::: "memory");
;             const unsigned og = xb_add(&bar[XB_TOP], 1u);
;             const unsigned tg = og / nx;
;             if (og + 1u == (tg + 1u) * nx) xb_add(&bar[XB_TOPGEN], 1u);
;             else XB_SPIN(xb_ld(&bar[XB_TOPGEN]) == tg, bar);
;             __builtin_amdgcn_fence(__ATOMIC_ACQUIRE, "agent");
;             xb_add(&bar[XB_XGEN(b.x)], 1u);
;             asm volatile("s_waitcnt vmcnt(0)" ::: "memory");
.LBB0_1835:
	s_or_b64 exec, exec, s[8:9]
	s_mov_b64 s[8:9], exec
	v_mbcnt_lo_u32_b32 v0, s8, 0
	v_mbcnt_hi_u32_b32 v0, s9, v0
	v_cmp_eq_u32_e32 vcc, 0, v0
	s_waitcnt vmcnt(0)
	buffer_inv sc1
	s_and_saveexec_b64 s[12:13], vcc
	s_cbranch_execz .LBB0_1837
	s_bcnt1_i32_b64 s0, s[8:9]
	v_mov_b32_e32 v0, 0x2000
	v_mov_b32_e32 v1, s0
.LBB0_1837:
	s_or_b64 exec, exec, s[12:13]
	s_waitcnt vmcnt(0)
